# v38 plus 8-workgroup row-tile group barriers instead of grid barriers between branch, w_out, up and down GEMMs
# baseline (speedup 1.0000x reference)
.LBB0_971:
	v_mbcnt_lo_u32_b32 v0, -1, 0
	v_mbcnt_hi_u32_b32 v0, -1, v0
	s_waitcnt vmcnt(0)
	v_readlane_b32 s0, v253, 11
	s_waitcnt lgkmcnt(0)
	s_barrier
	v_cmp_eq_u32_e32 vcc, s0, v0
	s_and_saveexec_b64 s[0:1], vcc
	s_cbranch_execz .LBB0_1023
	v_readlane_b32 s12, v253, 3
	s_waitcnt vmcnt(0) expcnt(0) lgkmcnt(0)
	s_nop 3
	s_lshr_b32 s13, s12, 6
	s_and_b32 s13, s13, 7
	s_lshr_b32 s12, s12, 4
	s_and_b32 s12, s12, 3
	s_lshl_b32 s12, s12, 3
	s_or_b32 s12, s12, s13
	s_lshl_b32 s12, s12, 8
	s_addk_i32 s12, 0x80
	v_mov_b32_e32 v1, s12
	v_mov_b32_e32 v4, 1
	buffer_wbl2 sc1
	s_waitcnt vmcnt(0)
	global_atomic_add v2, v1, v4, s[68:69] offset:-1024 sc0
	s_mov_b32 s13, 0
	s_waitcnt vmcnt(0)
	v_and_b32_e32 v2, -8, v2
	v_add_u32_e32 v2, 8, v2
.Lgb_g5_spin:
	global_load_dword v0, v1, s[68:69] offset:-1024 sc1
	s_add_i32 s13, s13, 1
	s_waitcnt vmcnt(0)
	v_cmp_lt_u32_e32 vcc, v0, v2
	s_cbranch_vccz .Lgb_g5_done
	s_cmp_lt_u32 s13, 0x10000
	s_cbranch_scc0 .Lgb_g5_done
	s_sleep 1
	s_branch .Lgb_g5_spin
.Lgb_g5_done:
	buffer_inv sc1
	s_waitcnt vmcnt(0)

.LBB0_1059:
	v_mbcnt_lo_u32_b32 v0, -1, 0
	v_mbcnt_hi_u32_b32 v0, -1, v0
	s_waitcnt vmcnt(0)
	v_readlane_b32 s0, v253, 11
	s_waitcnt lgkmcnt(0)
	s_barrier
	v_cmp_eq_u32_e32 vcc, s0, v0
	s_and_saveexec_b64 s[0:1], vcc
	v_readlane_b32 s42, v255, 50
	v_readlane_b32 s43, v255, 51
	s_cbranch_execz .LBB0_1111
	v_readlane_b32 s12, v253, 3
	s_waitcnt vmcnt(0) expcnt(0) lgkmcnt(0)
	s_nop 3
	s_lshr_b32 s13, s12, 6
	s_and_b32 s13, s13, 7
	s_lshr_b32 s12, s12, 4
	s_and_b32 s12, s12, 3
	s_lshl_b32 s12, s12, 3
	s_or_b32 s12, s12, s13
	s_lshl_b32 s12, s12, 8
	s_addk_i32 s12, 0x80
	v_mov_b32_e32 v1, s12
	v_mov_b32_e32 v4, 1
	buffer_wbl2 sc1
	s_waitcnt vmcnt(0)
	global_atomic_add v2, v1, v4, s[68:69] offset:-1024 sc0
	s_mov_b32 s13, 0
	s_waitcnt vmcnt(0)
	v_and_b32_e32 v2, -8, v2
	v_add_u32_e32 v2, 8, v2

.LBB0_1131:
	v_mbcnt_lo_u32_b32 v0, -1, 0
	v_mbcnt_hi_u32_b32 v0, -1, v0
	s_waitcnt vmcnt(0)
	v_readlane_b32 s0, v253, 11
	s_barrier
	s_nop 0
	v_cmp_eq_u32_e32 vcc, s0, v0
	s_and_saveexec_b64 s[0:1], vcc
	s_xor_b64 s[0:1], exec, s[0:1]
	s_cbranch_execz .LBB0_1184
	v_readlane_b32 s12, v253, 3
	s_waitcnt vmcnt(0) expcnt(0) lgkmcnt(0)
	s_nop 3
	s_lshr_b32 s13, s12, 6
	s_and_b32 s13, s13, 7
	s_lshr_b32 s12, s12, 4
	s_and_b32 s12, s12, 3
	s_lshl_b32 s12, s12, 3
	s_or_b32 s12, s12, s13
	s_lshl_b32 s12, s12, 8
	s_addk_i32 s12, 0x80
	v_mov_b32_e32 v1, s12
	v_mov_b32_e32 v4, 1
	buffer_wbl2 sc1
	s_waitcnt vmcnt(0)
	global_atomic_add v2, v1, v4, s[68:69] offset:-1024 sc0
	s_mov_b32 s13, 0
	s_waitcnt vmcnt(0)
	v_and_b32_e32 v2, -8, v2
	v_add_u32_e32 v2, 8, v2
